# placement sweep: both attention loop heads at 16 mod 64
# baseline (speedup 1.0000x reference)
.LBB0_505:
	v_add_f32_e32 v16, 0, v32
	v_add_f32_e32 v16, v33, v16
	v_add_f32_e32 v17, 0, v40
	v_add_f32_e32 v16, v34, v16
	v_add_f32_e32 v17, v41, v17
	v_add_f32_e32 v16, v35, v16
	v_add_f32_e32 v17, v42, v17
	v_add_f32_e32 v16, v36, v16
	v_add_f32_e32 v17, v43, v17
	v_add_f32_e32 v16, v37, v16
	v_add_f32_e32 v17, v44, v17
	v_add_f32_e32 v16, v38, v16
	v_add_f32_e32 v17, v45, v17
	v_add_f32_e32 v16, v39, v16
	v_add_f32_e32 v17, v46, v17
	v_add_f32_e32 v16, 0, v16
	v_add_f32_e32 v17, v47, v17
	v_add_f32_e32 v18, 0, v48
	v_add_f32_e32 v16, v17, v16
	v_add_f32_e32 v17, 0, v56
	v_add_f32_e32 v18, v49, v18
	v_add_f32_e32 v17, v57, v17
	v_add_f32_e32 v18, v50, v18
	v_add_f32_e32 v17, v58, v17
	v_add_f32_e32 v18, v51, v18
	v_add_f32_e32 v17, v59, v17
	v_add_f32_e32 v18, v52, v18
	v_add_f32_e32 v17, v60, v17
	v_add_f32_e32 v18, v53, v18
	v_add_f32_e32 v17, v61, v17
	v_add_f32_e32 v18, v54, v18
	s_waitcnt vmcnt(0)
	ds_write_b64 v216, v[64:65] offset:18432
	s_waitcnt lgkmcnt(0)
	ds_write_b64 v216, v[68:69] offset:27648
	ds_write2st64_b64 v217, v[66:67], v[70:71] offset0:36 offset1:54
	ds_write_b128 v213, v[144:147]
	v_add_f32_e32 v17, v62, v17
	v_add_f32_e32 v18, v55, v18
	s_waitcnt lgkmcnt(0)
	s_barrier
	v_add_f32_e32 v17, v63, v17
	v_add_f32_e32 v16, v18, v16
	v_mov_b32_e32 v31, 0
	v_cvt_pk_bf16_f32 v160, v32, v33
	v_cvt_pk_bf16_f32 v161, v34, v35
	v_cvt_pk_bf16_f32 v162, v36, v37
	v_cvt_pk_bf16_f32 v163, v38, v39
	v_cvt_pk_bf16_f32 v148, v40, v41
	v_cvt_pk_bf16_f32 v149, v42, v43
	v_cvt_pk_bf16_f32 v150, v44, v45
	v_cvt_pk_bf16_f32 v151, v46, v47
	v_cvt_pk_bf16_f32 v152, v48, v49
	v_cvt_pk_bf16_f32 v153, v50, v51
	v_cvt_pk_bf16_f32 v154, v52, v53
	v_cvt_pk_bf16_f32 v155, v54, v55
	v_add_f32_e32 v193, v17, v16
	v_cvt_pk_bf16_f32 v156, v56, v57
	v_cvt_pk_bf16_f32 v157, v58, v59
	v_cvt_pk_bf16_f32 v158, v60, v61
	v_cvt_pk_bf16_f32 v159, v62, v63
	s_andn2_b64 vcc, exec, s[2:3]
	s_cbranch_vccnz .LBB0_512
	v_mov_b32_e32 v32, 0
	s_mov_b32 s93, 0
	s_movk_i32 s15, 0x80
	s_mov_b64 s[6:7], 0x80
	v_mov_b32_e32 v33, v32
	v_mov_b32_e32 v34, v32
	v_mov_b32_e32 v35, v32
	v_mov_b32_e32 v36, v32
	v_mov_b32_e32 v37, v32
	v_mov_b32_e32 v38, v32
	v_mov_b32_e32 v39, v32
	v_mov_b32_e32 v40, v32
	v_mov_b32_e32 v41, v32
	v_mov_b32_e32 v42, v32
	v_mov_b32_e32 v43, v32
	v_mov_b32_e32 v44, v32
	v_mov_b32_e32 v45, v32
	v_mov_b32_e32 v46, v32
	v_mov_b32_e32 v47, v32
	v_mov_b32_e32 v64, v32
	v_mov_b32_e32 v65, v32
	v_mov_b32_e32 v66, v32
	v_mov_b32_e32 v67, v32
	v_mov_b32_e32 v68, v32
	v_mov_b32_e32 v69, v32
	v_mov_b32_e32 v70, v32
	v_mov_b32_e32 v71, v32
	v_mov_b32_e32 v72, v32
	v_mov_b32_e32 v73, v32
	v_mov_b32_e32 v74, v32
	v_mov_b32_e32 v75, v32
	v_mov_b32_e32 v76, v32
	v_mov_b32_e32 v77, v32
	v_mov_b32_e32 v78, v32
	v_mov_b32_e32 v79, v32
	v_mov_b32_e32 v48, v32
	v_mov_b32_e32 v49, v32
	v_mov_b32_e32 v50, v32
	v_mov_b32_e32 v51, v32
	v_mov_b32_e32 v52, v32
	v_mov_b32_e32 v53, v32
	v_mov_b32_e32 v54, v32
	v_mov_b32_e32 v55, v32
	v_mov_b32_e32 v56, v32
	v_mov_b32_e32 v57, v32
	v_mov_b32_e32 v58, v32
	v_mov_b32_e32 v59, v32
	v_mov_b32_e32 v60, v32
	v_mov_b32_e32 v61, v32
	v_mov_b32_e32 v62, v32
	v_mov_b32_e32 v63, v32
	v_mov_b32_e32 v16, v32
	v_mov_b32_e32 v17, v32
	v_mov_b32_e32 v18, v32
	v_mov_b32_e32 v19, v32
	v_mov_b32_e32 v20, v32
	v_mov_b32_e32 v21, v32
	v_mov_b32_e32 v22, v32
	v_mov_b32_e32 v23, v32
	v_mov_b32_e32 v24, v32
	v_mov_b32_e32 v25, v32
	v_mov_b32_e32 v26, v32
	v_mov_b32_e32 v27, v32
	v_mov_b32_e32 v28, v32
	v_mov_b32_e32 v29, v32
	v_mov_b32_e32 v30, v32
	v_mov_b32_e32 v31, v32
	v_mov_b32_e32 v142, 0
	s_branch .LBB0_508
	.p2align 6
	s_nop 0
	s_nop 0
	s_nop 0
	s_nop 0
.LBB0_507:
	s_waitcnt lgkmcnt(5)
	v_mfma_f32_32x32x16_bf16 v[32:47], v[222:225], v[152:155], v[32:47]
	ds_read_b128 v[246:249], v192 offset:27744
	v_exp_f32_e32 v80, v80
	v_exp_f32_e32 v81, v81
	s_and_b32 s16, s15, 64
	s_mulk_i32 s16, 0x90
	v_add_f32_e32 v193, v80, v193
	v_add_f32_e32 v142, v81, v142
	v_add_u32_e32 v170, s16, v208
	s_waitcnt lgkmcnt(5)
	v_mfma_f32_32x32x16_bf16 v[64:79], v[226:229], v[152:155], v[64:79]
	ds_read_b128 v[250:253], v192 offset:32352
	v_exp_f32_e32 v82, v82
	v_exp_f32_e32 v83, v83
	s_add_i32 s93, s93, 1
	s_and_b32 s16, s93, 1
	v_add_f32_e32 v193, v82, v193
	v_add_f32_e32 v142, v83, v142
	s_mul_i32 s17, s16, 0x4800
	s_waitcnt lgkmcnt(5)
	v_mfma_f32_32x32x16_bf16 v[48:63], v[230:233], v[152:155], v[48:63]
	ds_read_b128 v[222:225], v192 offset:18432
	v_exp_f32_e32 v84, v84
	v_exp_f32_e32 v85, v85
	s_mulk_i32 s16, 0x2400
	s_add_i32 s15, s15, 64
	s_add_u32 s6, s6, 0x80
	s_addc_u32 s7, s7, 0
	s_cmp_eq_u32 s14, s93
	v_add_f32_e32 v193, v84, v193
	v_add_f32_e32 v142, v85, v142
	s_waitcnt lgkmcnt(5)
	v_mfma_f32_32x32x16_bf16 v[16:31], v[234:237], v[152:155], v[16:31]
	ds_read_b128 v[226:229], v192 offset:23040
	v_exp_f32_e32 v86, v86
	v_exp_f32_e32 v87, v87
	v_add_f32_e32 v193, v86, v193
	v_add_f32_e32 v142, v87, v142
	v_cvt_pk_bf16_f32 v152, v80, v81
	v_cvt_pk_bf16_f32 v153, v82, v83
	v_cvt_pk_bf16_f32 v154, v84, v85
	v_cvt_pk_bf16_f32 v155, v86, v87
	s_waitcnt lgkmcnt(5)
	v_mfma_f32_32x32x16_bf16 v[32:47], v[238:241], v[156:159], v[32:47]
	ds_read_b128 v[230:233], v192 offset:27648
	v_exp_f32_e32 v88, v88
	v_exp_f32_e32 v89, v89
	v_add_f32_e32 v193, v88, v193
	v_add_f32_e32 v142, v89, v142
	s_waitcnt lgkmcnt(5)
	v_mfma_f32_32x32x16_bf16 v[64:79], v[242:245], v[156:159], v[64:79]
	ds_read_b128 v[234:237], v192 offset:32256
	v_exp_f32_e32 v90, v90
	v_exp_f32_e32 v91, v91
	v_add_f32_e32 v193, v90, v193
	v_add_f32_e32 v142, v91, v142
	s_waitcnt lgkmcnt(5)
	v_mfma_f32_32x32x16_bf16 v[48:63], v[246:249], v[156:159], v[48:63]
	ds_read_b128 v[238:241], v192 offset:18464
	v_exp_f32_e32 v92, v92
	v_exp_f32_e32 v93, v93
	v_add_f32_e32 v193, v92, v193
	v_add_f32_e32 v142, v93, v142
	s_waitcnt lgkmcnt(5)
	v_mfma_f32_32x32x16_bf16 v[16:31], v[250:253], v[156:159], v[16:31]
	ds_read_b128 v[242:245], v192 offset:23072
	v_exp_f32_e32 v94, v94
	v_exp_f32_e32 v95, v95
	v_add_f32_e32 v193, v94, v193
	v_add_f32_e32 v142, v95, v142
	v_cvt_pk_bf16_f32 v156, v88, v89
	v_cvt_pk_bf16_f32 v157, v90, v91
	v_cvt_pk_bf16_f32 v158, v92, v93
	v_cvt_pk_bf16_f32 v159, v94, v95
	s_waitcnt lgkmcnt(5)
	v_mfma_f32_32x32x16_bf16 v[32:47], v[222:225], v[160:163], v[32:47]
	ds_read_b128 v[246:249], v192 offset:27680
	v_exp_f32_e32 v96, v96
	v_exp_f32_e32 v97, v97
	v_add_f32_e32 v193, v96, v193
	v_add_f32_e32 v142, v97, v142
	s_waitcnt lgkmcnt(5)
	v_mfma_f32_32x32x16_bf16 v[64:79], v[226:229], v[160:163], v[64:79]
	ds_read_b128 v[250:253], v192 offset:32288
	v_exp_f32_e32 v98, v98
	v_exp_f32_e32 v99, v99
	v_add_f32_e32 v193, v98, v193
	v_add_f32_e32 v142, v99, v142
	s_waitcnt lgkmcnt(5)
	v_mfma_f32_32x32x16_bf16 v[48:63], v[230:233], v[160:163], v[48:63]
	ds_read_b128 v[222:225], v170
	v_exp_f32_e32 v100, v100
	v_exp_f32_e32 v101, v101
	v_add_f32_e32 v193, v100, v193
	v_add_f32_e32 v142, v101, v142
	s_waitcnt lgkmcnt(5)
	v_mfma_f32_32x32x16_bf16 v[16:31], v[234:237], v[160:163], v[16:31]
	ds_read_b128 v[226:229], v170 offset:4608
	v_exp_f32_e32 v102, v102
	v_exp_f32_e32 v103, v103
	v_add_f32_e32 v193, v102, v193
	v_add_f32_e32 v142, v103, v142
	v_cvt_pk_bf16_f32 v160, v96, v97
	v_cvt_pk_bf16_f32 v161, v98, v99
	v_cvt_pk_bf16_f32 v162, v100, v101
	v_cvt_pk_bf16_f32 v163, v102, v103
	s_waitcnt lgkmcnt(5)
	v_mfma_f32_32x32x16_bf16 v[32:47], v[238:241], v[148:151], v[32:47]
	ds_read_b128 v[230:233], v170 offset:4640
	v_exp_f32_e32 v104, v104
	v_exp_f32_e32 v105, v105
	v_add_f32_e32 v193, v104, v193
	v_add_f32_e32 v142, v105, v142
	s_waitcnt lgkmcnt(5)
	v_mfma_f32_32x32x16_bf16 v[64:79], v[242:245], v[148:151], v[64:79]
	ds_read_b128 v[234:237], v170 offset:4672
	v_exp_f32_e32 v106, v106
	v_exp_f32_e32 v107, v107
	v_add_f32_e32 v193, v106, v193
	v_add_f32_e32 v142, v107, v142
	s_waitcnt lgkmcnt(5)
	v_mfma_f32_32x32x16_bf16 v[48:63], v[246:249], v[148:151], v[48:63]
	ds_read_b128 v[238:241], v170 offset:4704
	v_exp_f32_e32 v108, v108
	v_exp_f32_e32 v109, v109
	v_add_f32_e32 v193, v108, v193
	v_add_f32_e32 v142, v109, v142
	s_waitcnt lgkmcnt(5)
	v_mfma_f32_32x32x16_bf16 v[16:31], v[250:253], v[148:151], v[16:31]
	ds_read_b128 v[242:245], v170 offset:32
	v_exp_f32_e32 v110, v110
	v_exp_f32_e32 v111, v111
	v_add_f32_e32 v193, v110, v193
	v_add_f32_e32 v142, v111, v142
	v_cvt_pk_bf16_f32 v148, v104, v105
	v_cvt_pk_bf16_f32 v149, v106, v107
	v_cvt_pk_bf16_f32 v150, v108, v109
	v_cvt_pk_bf16_f32 v151, v110, v111
	s_waitcnt lgkmcnt(5)
	v_mfma_f32_32x32x16_bf16 v[96:111], v[222:225], v[124:127], 0
	ds_read_b128 v[246:249], v170 offset:64
	s_waitcnt lgkmcnt(5)
	v_mfma_f32_32x32x16_bf16 v[80:95], v[226:229], v[124:127], 0
	ds_read_b128 v[250:253], v170 offset:96
	v_add_u32_e32 v168, s17, v212
	v_lshl_add_u32 v140, v210, 1, v168
	s_waitcnt vmcnt(0)
	ds_write_b64 v140, v[128:129] offset:18432
	v_lshl_add_u32 v128, v211, 1, v168
	ds_write_b64 v140, v[132:133] offset:27648
	ds_write2st64_b64 v128, v[130:131], v[134:135] offset0:36 offset1:54
	v_add_u32_e32 v128, s16, v213
	ds_write_b128 v128, v[144:147]
	s_waitcnt lgkmcnt(0)
	s_barrier
	s_cbranch_scc1 .Latt_exit_a
	s_andn2_b32 s16, 0x80, s6
	s_mulk_i32 s16, 0x90
	v_add_u32_e32 v192, s16, v208
	ds_read_b128 v[222:225], v192 offset:18496
	ds_read_b128 v[226:229], v192 offset:23104
	v_mfma_f32_32x32x16_bf16 v[80:95], v[230:233], v[120:123], v[80:95]
	ds_read_b128 v[230:233], v192 offset:27712
	s_add_i32 s16, s93, 3
	s_cmp_lt_u32 s16, s13
	s_cselect_b32 s86, s16, s92
	s_add_u32 s16, s90, s6
	s_addc_u32 s17, s91, s7
	global_load_dwordx4 v[128:131], v184, s[16:17]
	v_mfma_f32_32x32x16_bf16 v[80:95], v[234:237], v[116:119], v[80:95]
	ds_read_b128 v[234:237], v192 offset:32320
	s_add_u32 s16, s0, s6
	s_addc_u32 s17, s1, s7
	global_load_dwordx4 v[132:135], v184, s[16:17]
	v_mfma_f32_32x32x16_bf16 v[80:95], v[238:241], v[112:115], v[80:95]
	ds_read_b128 v[238:241], v192 offset:18528
	s_lshl_b64 s[16:17], s[86:87], 17
	s_add_u32 s16, s84, s16
	s_addc_u32 s17, s85, s17
	global_load_dwordx4 v[144:147], v182, s[16:17]
	v_mfma_f32_32x32x16_bf16 v[96:111], v[242:245], v[120:123], v[96:111]
	ds_read_b128 v[242:245], v192 offset:23136
	v_mfma_f32_32x32x16_bf16 v[96:111], v[246:249], v[116:119], v[96:111]
	v_mfma_f32_32x32x16_bf16 v[96:111], v[250:253], v[112:115], v[96:111]
	s_branch .Latt_mask_a
